# scan phase queue B: the next job id is requested while the current job runs (atomic latency off the pop path)
# baseline (speedup 1.0000x reference)
.LBB0_421:
	s_or_b64 exec, exec, s[0:1]
	s_mov_b32 s98, 0
	v_writelane_b32 v250, s98, 42
	v_writelane_b32 v250, s98, 43
	v_readlane_b32 s6, v252, 0
	v_readlane_b32 s7, v252, 1
	s_mov_b64 s[0:1], s[6:7]
	v_readlane_b32 s8, v250, 5
	s_waitcnt lgkmcnt(0)
	s_barrier
	v_readlane_b32 s9, v250, 6
	s_load_dwordx2 s[0:1], s[0:1], 0x158
	s_and_b64 s[4:5], s[8:9], exec
	s_mov_b64 s[4:5], s[6:7]
	s_load_dwordx2 s[4:5], s[4:5], 0x158
	s_cselect_b32 s6, 64, 0
	v_writelane_b32 v250, s6, 12
	s_lshl_b32 s6, s6, 2
	s_waitcnt lgkmcnt(0)
	s_add_u32 s0, s0, s6
	s_addc_u32 s1, s1, 0
	v_writelane_b32 v250, s0, 13
	v_mov_b32_e32 v0, v162
	s_mov_b32 s71, s73
	v_writelane_b32 v250, s1, 14
	s_add_u32 s0, s4, s6
	s_addc_u32 s1, s5, 0
	v_writelane_b32 v250, s0, 15
	v_sub_u32_e32 v0, 0, v0
	v_readlane_b32 s24, v252, 28
	v_writelane_b32 v250, s1, 16
	v_readlane_b32 s0, v251, 21
	v_readlane_b32 s1, v251, 22
	s_nop 0
	v_cmp_eq_u32_e64 s[0:1], s0, v0
	s_nop 1
	v_writelane_b32 v250, s0, 10
	s_nop 1
	v_writelane_b32 v250, s1, 11
	s_and_b64 s[0:1], s[8:9], exec
	s_cselect_b32 s0, 0x4000, 0
	v_writelane_b32 v250, s0, 5
	s_cselect_b32 s0, 8, 0
	v_writelane_b32 v250, s0, 17
	s_cselect_b32 s0, 0x800, 0
	v_writelane_b32 v250, s0, 18
	s_cselect_b32 s0, 0x80, 0
	s_mov_b32 s1, s73
	v_writelane_b32 v250, s0, 19
	s_nop 1
	v_writelane_b32 v250, s1, 20
	s_cselect_b32 s0, 0x400, 0
	v_writelane_b32 v250, s0, 21
	s_cselect_b32 s0, 0x200000, 0
	v_writelane_b32 v250, s0, 22
	s_cselect_b32 s0, 0x200, 0
	v_writelane_b32 v250, s0, 23
	v_writelane_b32 v250, s70, 8
	s_nop 1
	v_writelane_b32 v250, s71, 9
	s_branch .LBB0_425

.LBB0_431:
	s_mov_b64 s[36:37], 0
	s_mov_b32 s28, 0
	s_andn2_b64 vcc, exec, s[0:1]
	s_mov_b64 s[0:1], 0
	s_cbranch_vccnz .LBB0_446
	s_barrier
	s_mov_b64 s[0:1], exec
	v_readlane_b32 s4, v250, 10
	v_readlane_b32 s5, v250, 11
	s_and_b64 s[4:5], s[0:1], s[4:5]
	s_mov_b64 exec, s[4:5]
	s_cbranch_execz .LBB0_436
	s_mov_b64 s[6:7], exec
	v_mbcnt_lo_u32_b32 v0, s6, 0
	v_mbcnt_hi_u32_b32 v0, s7, v0
	v_cmp_eq_u32_e32 vcc, 0, v0
	s_and_saveexec_b64 s[4:5], vcc
	s_cbranch_execz .LBB0_435
	s_bcnt1_i32_b64 s6, s[6:7]
	v_mov_b32_e32 v2, s6
	v_readlane_b32 s6, v250, 15
	v_readlane_b32 s7, v250, 16
	v_readlane_b32 s98, v250, 43
	s_nop 3
	s_cmp_eq_u32 s98, 0
	s_cbranch_scc1 .Lqb_atomic
	s_waitcnt vmcnt(0)
	v_readlane_b32 s99, v250, 44
	s_nop 3
	v_mov_b32_e32 v2, s99
	s_branch .LBB0_435
.Lqb_atomic:
	s_nop 4
	global_atomic_add v2, v1, v2, s[6:7] offset:512 sc0
.LBB0_435:
	s_or_b64 exec, exec, s[4:5]
	s_waitcnt vmcnt(0)
	v_readfirstlane_b32 s4, v2
	s_nop 1
	v_add_u32_e32 v0, s4, v0
	v_readlane_b32 s6, v250, 15
	v_readlane_b32 s7, v250, 16
	s_mov_b64 s[100:101], exec
	s_mov_b32 exec_lo, 0
	s_mov_b32 exec_hi, 0x1000
	v_mov_b32_e32 v2, 1
	s_nop 4
	global_atomic_add v250, v1, v2, s[6:7] offset:512 sc0
	s_mov_b64 exec, s[100:101]
	s_mov_b32 s98, 1
	s_nop 0
	v_writelane_b32 v250, s98, 43
	v_readlane_b32 s4, v251, 42
	s_nop 1
	v_mov_b32_e32 v2, s4
	ds_write_b32 v2, v0
